# hot loop heads (PEER gather main loop, three GEMM k-loops) aligned to 64 bytes
# baseline (speedup 1.0000x reference)
; DEV int ltid() { int t = threadIdx.x; asm volatile("" : "+v"(t)); return t; }
; template <class AF, class EPI>
; DEV void gemm_tile256(AF aptr, const u16* Bt, int ldb, int K, EPI epi, char* smem) {
;   const int tid = ltid(), wid = tid >> 6, lane = tid & 63, wr = wid >> 1, wc = wid & 1, fr = lane & 15, fq = lane >> 4;
;   f32x4 acc[8][4];
; #pragma unroll
;   for (int m = 0; m < 8; ++m)
; #pragma unroll
;     for (int n = 0; n < 4; ++n) acc[m][n] = f32x4{0.f, 0.f, 0.f, 0.f};
;   const int nk = K / 32;
;   auto stage = [&](int kt, int buf) {
;     char* SA = smem + buf * 24576;
;     char* SB = SA + 16384;
; #pragma unroll
;     for (int i = 0; i < 4; ++i) {
;       int bo = tid * 16 + i * 4096, r = bo >> 6, c = (bo & 63) >> 1;
;       __builtin_amdgcn_global_load_lds((const unsigned*)aptr(r, kt * 32 + c), (__attribute__((address_space(3))) unsigned*)(SA + bo), 16, 0, 0);
;     }
; #pragma unroll
;     for (int i = 0; i < 2; ++i) {
;       int bo = tid * 16 + i * 4096, r = bo >> 6, c = (bo & 63) >> 1;
;       __builtin_amdgcn_global_load_lds((const unsigned*)(Bt + (size_t)r * ldb + kt * 32 + c), (__attribute__((address_space(3))) unsigned*)(SB + bo), 16, 0, 0);
;     }
;   };
;   asm volatile("s_waitcnt vmcnt(0)" ::: "memory");
;   __syncthreads();
;   stage(0, 0);
;   stage(1, 1);
;   const unsigned lbase = (unsigned)(size_t)(const __attribute__((address_space(3))) char*)smem;
;   const unsigned aoff = lbase + (wr * 128 + fr) * 64 + fq * 16, boff = lbase + 16384 + (wc * 64 + fr) * 64 + fq * 16;
; __global__ void __launch_bounds__(256, 2) fwd_megakernel(Params p) {
;     ...
;   for (int jt = (bid >> 3); jt < 8 * 37; jt += (nb >> 3)) {
;     const int pn = jt >> 3, pm = (bid & 7) * 8 + (jt & 7);
;     const u16* A = p.h + (size_t)pm * 256 * 2048;
;     gemm_tile256([&](int r, int k) { return A + (size_t)r * 2048 + k; }, p.Wt_in + (size_t)pn * 128 * 2048, 2048, 2048,
.LBB0_247:
	s_and_b32 s57, s3, 7
	s_lshl_b32 s0, s57, 19
	s_add_i32 s0, s6, s0
	s_lshr_b32 s44, s0, 5
	s_and_b32 s0, s93, 7
	s_or_b32 s56, s0, s4
	v_readlane_b32 s16, v255, 9
	v_mov_b32_e32 v144, v0
	s_ashr_i32 s38, s93, 3
	s_lshl_b32 s0, s56, 14
	v_readlane_b32 s20, v255, 13
	v_readlane_b32 s21, v255, 14
	v_ashrrev_i32_e32 v2, 2, v144
	s_add_u32 s40, s20, s0
	v_lshlrev_b32_e32 v148, 4, v144
	v_ashrrev_i32_e32 v3, 31, v2
	s_addc_u32 s41, s21, 0
	s_ashr_i32 s39, s38, 31
	v_lshlrev_b64 v[2:3], 12, v[2:3]
	v_lshrrev_b64 v[246:247], 6, v[2:3]
	s_mov_b64 s[86:87], 0x100000
	s_mov_b64 s[88:89], 0x4a000
	v_add_u32_e32 v10, 0x1000, v148
	s_lshl_b64 s[0:1], s[38:39], 13
	v_lshl_add_u64 v[4:5], s[40:41], 0, v[246:247]
	v_and_b32_e32 v134, 48, v148
	v_and_b32_e32 v253, 32, v144
	v_xor_b32_e32 v134, v134, v253
	v_readfirstlane_b32 s39, v148
	v_ashrrev_i32_e32 v6, 6, v10
	v_add_u32_e32 v14, 0x2000, v148
	v_readlane_b32 s17, v255, 10
	v_readlane_b32 s18, v255, 11
	v_readlane_b32 s19, v255, 12
	v_readlane_b32 s22, v255, 15
	v_readlane_b32 s23, v255, 16
	v_readlane_b32 s24, v255, 17
	v_readlane_b32 s25, v255, 18
	v_readlane_b32 s26, v255, 19
	v_readlane_b32 s27, v255, 20
	v_readlane_b32 s28, v255, 21
	v_readlane_b32 s29, v255, 22
	v_readlane_b32 s30, v255, 23
	v_readlane_b32 s31, v255, 24
	v_lshl_add_u64 v[4:5], v[4:5], 0, v[134:135]
	s_mov_b32 m0, s39
	v_ashrrev_i32_e32 v7, 31, v6
	v_readfirstlane_b32 s39, v10
	v_ashrrev_i32_e32 v10, 6, v14
	v_add_u32_e32 v18, 0x3000, v148
	v_readlane_b32 s16, v254, 4
	s_waitcnt vmcnt(0)
	s_barrier
; template <class AF, class EPI>
; DEV void gemm_tile256(AF aptr, const u16* Bt, int ldb, int K, EPI epi, char* smem) {
;     ...
;   f32x4 acc[8][4];
; #pragma unroll
;   for (int m = 0; m < 8; ++m)
; #pragma unroll
;     for (int n = 0; n < 4; ++n) acc[m][n] = f32x4{0.f, 0.f, 0.f, 0.f};
;   const int nk = K / 32;
;   auto stage = [&](int kt, int buf) {
;     char* SA = smem + buf * 24576;
;     char* SB = SA + 16384;
; #pragma unroll
;     for (int i = 0; i < 4; ++i) {
;       int bo = tid * 16 + i * 4096, r = bo >> 6, c = (bo & 63) >> 1;
;       __builtin_amdgcn_global_load_lds((const unsigned*)aptr(r, kt * 32 + c), (__attribute__((address_space(3))) unsigned*)(SA + bo), 16, 0, 0);
;     }
; #pragma unroll
;     for (int i = 0; i < 2; ++i) {
;       int bo = tid * 16 + i * 4096, r = bo >> 6, c = (bo & 63) >> 1;
;       __builtin_amdgcn_global_load_lds((const unsigned*)(Bt + (size_t)r * ldb + kt * 32 + c), (__attribute__((address_space(3))) unsigned*)(SB + bo), 16, 0, 0);
;     }
;   };
;   asm volatile("s_waitcnt vmcnt(0)" ::: "memory");
;   __syncthreads();
;   stage(0, 0);
;   stage(1, 1);
;   const unsigned lbase = (unsigned)(size_t)(const __attribute__((address_space(3))) char*)smem;
;   const unsigned aoff = lbase + (wr * 128 + fr) * 64 + fq * 16, boff = lbase + 16384 + (wc * 64 + fr) * 64 + fq * 16;
	global_load_lds_dwordx4 v[4:5], off
	v_lshlrev_b64 v[6:7], 12, v[6:7]
	v_lshrrev_b64 v[248:249], 6, v[6:7]
	s_mov_b32 m0, s39
	v_ashrrev_i32_e32 v11, 31, v10
	v_readfirstlane_b32 s39, v14
	v_ashrrev_i32_e32 v14, 6, v18
	v_readlane_b32 s26, v254, 14
	v_lshl_add_u64 v[8:9], s[40:41], 0, v[248:249]
	v_lshlrev_b64 v[10:11], 6, v[10:11]
	v_ashrrev_i32_e32 v15, 31, v14
	v_readlane_b32 s27, v254, 15
	s_add_u32 s42, s26, s0
	v_lshl_add_u64 v[8:9], v[8:9], 0, v[134:135]
	v_lshl_add_u64 v[12:13], s[40:41], 0, v[10:11]
	v_lshlrev_b64 v[14:15], 6, v[14:15]
	s_addc_u32 s43, s27, s1
	global_load_lds_dwordx4 v[8:9], off
	v_lshl_add_u64 v[12:13], v[12:13], 0, v[134:135]
	s_mov_b32 m0, s39
	v_lshl_add_u64 v[16:17], s[40:41], 0, v[14:15]
	v_readfirstlane_b32 s39, v18
	v_add_u32_e32 v20, 0x4000, v148
	global_load_lds_dwordx4 v[12:13], off
	v_lshl_add_u64 v[16:17], v[16:17], 0, v[134:135]
	s_mov_b32 m0, s39
	v_lshl_add_u64 v[18:19], s[42:43], 0, v[246:247]
	v_readfirstlane_b32 s39, v20
	v_add_u32_e32 v22, 0x5000, v148
	global_load_lds_dwordx4 v[16:17], off
	v_lshl_add_u64 v[18:19], v[18:19], 0, v[134:135]
	s_mov_b32 m0, s39
	v_lshl_add_u64 v[20:21], s[42:43], 0, v[248:249]
	v_readfirstlane_b32 s39, v22
	v_add_u32_e32 v22, 0x6000, v148
	global_load_lds_dwordx4 v[18:19], off
	v_lshl_add_u64 v[20:21], v[20:21], 0, v[134:135]
	s_mov_b32 m0, s39
	v_readfirstlane_b32 s39, v22
	global_load_lds_dwordx4 v[20:21], off
	v_lshl_add_u64 v[4:5], v[4:5], 0, s[86:87]
	s_mov_b32 m0, s39
	s_add_u32 s40, s5, s44
	global_load_lds_dwordx4 v[4:5], off
	v_lshl_add_u64 v[4:5], v[8:9], 0, s[86:87]
	v_add_u32_e32 v8, 0x7000, v148
	v_bfe_u32 v147, v144, 4, 2
	v_readfirstlane_b32 s39, v8
	v_add_u32_e32 v8, 0x8000, v148
	s_mov_b32 m0, s39
	v_readfirstlane_b32 s39, v8
	v_add_u32_e32 v8, 0x9000, v148
	global_load_lds_dwordx4 v[4:5], off
	v_lshl_add_u64 v[4:5], v[12:13], 0, s[86:87]
	s_mov_b32 m0, s39
	v_readfirstlane_b32 s39, v8
	v_add_u32_e32 v8, 0xa000, v148
	global_load_lds_dwordx4 v[4:5], off
	v_lshl_add_u64 v[4:5], v[16:17], 0, s[86:87]
	s_mov_b32 m0, s39
	v_readfirstlane_b32 s39, v8
	v_add_u32_e32 v8, 0xb000, v148
	global_load_lds_dwordx4 v[4:5], off
	v_lshl_add_u64 v[4:5], v[18:19], 0, s[88:89]
	s_mov_b32 m0, s39
	v_readfirstlane_b32 s39, v8
	global_load_lds_dwordx4 v[4:5], off
	v_lshl_add_u64 v[4:5], v[20:21], 0, s[88:89]
	s_mov_b32 m0, s39
	s_addc_u32 s41, s76, 0
	global_load_lds_dwordx4 v[4:5], off
	v_bfe_u32 v145, v144, 6, 1
	v_ashrrev_i32_e32 v159, 7, v144
	v_and_b32_e32 v146, 15, v144
	v_lshlrev_b32_e32 v8, 4, v147
	v_lshlrev_b32_e32 v253, 2, v144
	v_and_b32_e32 v253, 32, v253
	v_xor_b32_e32 v8, v8, v253
	s_add_u32 s0, s7, s0
	v_lshlrev_b32_e32 v4, 13, v159
	v_lshlrev_b32_e32 v5, 6, v146
	v_lshl_or_b32 v9, v145, 12, v8
	s_movk_i32 s39, 0x4000
	v_or_b32_e32 v2, v2, v134
	v_or_b32_e32 v6, v6, v134
	v_or_b32_e32 v10, v10, v134
	v_or_b32_e32 v14, v14, v134
	s_addc_u32 s1, s8, s1
	v_or3_b32 v149, v4, v8, v5
	v_or3_b32 v150, v5, v9, s39
	v_or_b32_e32 v246, v246, v134
	v_or_b32_e32 v248, v248, v134
	v_lshl_add_u64 v[130:131], s[40:41], 0, v[246:247]
	v_lshl_add_u64 v[132:133], s[40:41], 0, v[248:249]
	v_lshl_add_u64 v[136:137], s[40:41], 0, v[10:11]
	v_lshl_add_u64 v[138:139], s[40:41], 0, v[14:15]
	v_lshl_add_u64 v[140:141], s[0:1], 0, v[248:249]
	v_lshl_add_u64 v[142:143], s[0:1], 0, v[246:247]
	s_mov_b64 s[0:1], 0
	s_mov_b32 s39, 0
	s_mov_b32 s42, 0
	v_mov_b32_e32 v2, 0
	v_mov_b32_e32 v3, v135
	v_mov_b32_e32 v4, v135
	v_mov_b32_e32 v5, v135
	v_mov_b32_e32 v6, 0
	v_mov_b32_e32 v7, v135
	v_mov_b32_e32 v8, v135
	v_mov_b32_e32 v9, v135
	v_mov_b32_e32 v10, 0
	v_mov_b32_e32 v11, v135
	v_mov_b32_e32 v12, v135
	v_mov_b32_e32 v13, v135
	v_mov_b32_e32 v14, 0
	v_mov_b32_e32 v15, v135
	v_mov_b32_e32 v16, v135
	v_mov_b32_e32 v17, v135
	v_mov_b32_e32 v18, 0
	v_mov_b32_e32 v19, v135
	v_mov_b32_e32 v20, v135
	v_mov_b32_e32 v21, v135
	v_mov_b32_e32 v22, 0
	v_mov_b32_e32 v23, v135
	v_mov_b32_e32 v24, v135
	v_mov_b32_e32 v25, v135
	v_mov_b32_e32 v26, 0
	v_mov_b32_e32 v27, v135
	v_mov_b32_e32 v28, v135
	v_mov_b32_e32 v29, v135
	v_mov_b32_e32 v30, 0
	v_mov_b32_e32 v31, v135
	v_mov_b32_e32 v32, v135
	v_mov_b32_e32 v33, v135
	v_mov_b32_e32 v34, 0
	v_mov_b32_e32 v35, v135
	v_mov_b32_e32 v36, v135
	v_mov_b32_e32 v37, v135
	v_mov_b32_e32 v38, 0
	v_mov_b32_e32 v39, v135
	v_mov_b32_e32 v40, v135
	v_mov_b32_e32 v41, v135
	v_mov_b32_e32 v42, 0
	v_mov_b32_e32 v43, v135
	v_mov_b32_e32 v44, v135
	v_mov_b32_e32 v45, v135
	v_mov_b32_e32 v94, 0
	v_mov_b32_e32 v95, v135
	v_mov_b32_e32 v96, v135
	v_mov_b32_e32 v97, v135
	v_mov_b32_e32 v98, 0
	v_mov_b32_e32 v99, v135
	v_mov_b32_e32 v100, v135
	v_mov_b32_e32 v101, v135
	v_mov_b32_e32 v102, 0
	v_mov_b32_e32 v103, v135
	v_mov_b32_e32 v104, v135
	v_mov_b32_e32 v105, v135
	v_mov_b32_e32 v106, 0
	v_mov_b32_e32 v107, v135
	v_mov_b32_e32 v108, v135
	v_mov_b32_e32 v109, v135
	v_mov_b32_e32 v110, 0
	v_mov_b32_e32 v111, v135
	v_mov_b32_e32 v112, v135
	v_mov_b32_e32 v113, v135
	v_mov_b32_e32 v114, 0
	v_mov_b32_e32 v115, v135
	v_mov_b32_e32 v116, v135
	v_mov_b32_e32 v117, v135
	v_mov_b32_e32 v118, 0
	v_mov_b32_e32 v119, v135
	v_mov_b32_e32 v120, v135
	v_mov_b32_e32 v121, v135
	v_mov_b32_e32 v122, 0
	v_mov_b32_e32 v123, v135
	v_mov_b32_e32 v124, v135
	v_mov_b32_e32 v125, v135
	v_mov_b32_e32 v126, 0
	v_mov_b32_e32 v127, v135
	v_mov_b32_e32 v128, v135
	v_mov_b32_e32 v129, v135
	v_mov_b32_e32 v46, 0
	v_mov_b32_e32 v47, v135
	v_mov_b32_e32 v48, v135
	v_mov_b32_e32 v49, v135
	v_mov_b32_e32 v50, 0
	v_mov_b32_e32 v51, v135
	v_mov_b32_e32 v52, v135
	v_mov_b32_e32 v53, v135
	v_mov_b32_e32 v54, 0
	v_mov_b32_e32 v55, v135
	v_mov_b32_e32 v56, v135
	v_mov_b32_e32 v57, v135
	v_mov_b32_e32 v58, 0
	v_mov_b32_e32 v59, v135
	v_mov_b32_e32 v60, v135
	v_mov_b32_e32 v61, v135
	v_mov_b32_e32 v62, 0
	v_mov_b32_e32 v63, v135
	v_mov_b32_e32 v64, v135
	v_mov_b32_e32 v65, v135
	v_mov_b32_e32 v66, 0
	v_mov_b32_e32 v67, v135
	v_mov_b32_e32 v68, v135
	v_mov_b32_e32 v69, v135
	v_mov_b32_e32 v70, 0
	v_mov_b32_e32 v71, v135
	v_mov_b32_e32 v72, v135
	v_mov_b32_e32 v73, v135
	v_mov_b32_e32 v74, 0
	v_mov_b32_e32 v75, v135
	v_mov_b32_e32 v76, v135
	v_mov_b32_e32 v77, v135
	v_mov_b32_e32 v78, 0
	v_mov_b32_e32 v79, v135
	v_mov_b32_e32 v80, v135
	v_mov_b32_e32 v81, v135
	v_mov_b32_e32 v82, 0
	v_mov_b32_e32 v83, v135
	v_mov_b32_e32 v84, v135
	v_mov_b32_e32 v85, v135
	v_mov_b32_e32 v86, 0
	v_mov_b32_e32 v87, v135
	v_mov_b32_e32 v88, v135
	v_mov_b32_e32 v89, v135
	v_mov_b32_e32 v90, 0
	v_mov_b32_e32 v91, v135
	v_mov_b32_e32 v92, v135
	v_mov_b32_e32 v93, v135
	v_readlane_b32 s17, v254, 5
	v_readlane_b32 s18, v254, 6
	v_readlane_b32 s19, v254, 7
	v_readlane_b32 s20, v254, 8
	v_readlane_b32 s21, v254, 9
	v_readlane_b32 s22, v254, 10
	v_readlane_b32 s23, v254, 11
	v_readlane_b32 s24, v254, 12
	v_readlane_b32 s25, v254, 13
	v_readlane_b32 s28, v254, 16
	v_readlane_b32 s29, v254, 17
	v_readlane_b32 s30, v254, 18
	v_readlane_b32 s31, v254, 19
	s_branch .LBB0_249
	.p2align 6

; DEV int ltid() { int t = threadIdx.x; asm volatile("" : "+v"(t)); return t; }
; template <class AF, class EPI>
; DEV void gemm_tile256(AF aptr, const u16* Bt, int ldb, int K, EPI epi, char* smem) {
;   const int tid = ltid(), wid = tid >> 6, lane = tid & 63, wr = wid >> 1, wc = wid & 1, fr = lane & 15, fq = lane >> 4;
;   f32x4 acc[8][4];
; #pragma unroll
;   for (int m = 0; m < 8; ++m)
; #pragma unroll
;     for (int n = 0; n < 4; ++n) acc[m][n] = f32x4{0.f, 0.f, 0.f, 0.f};
;   const int nk = K / 32;
;   auto stage = [&](int kt, int buf) {
;     char* SA = smem + buf * 24576;
;     char* SB = SA + 16384;
; #pragma unroll
;     for (int i = 0; i < 4; ++i) {
;       int bo = tid * 16 + i * 4096, r = bo >> 6, c = (bo & 63) >> 1;
;       __builtin_amdgcn_global_load_lds((const unsigned*)aptr(r, kt * 32 + c), (__attribute__((address_space(3))) unsigned*)(SA + bo), 16, 0, 0);
;     }
; #pragma unroll
;     for (int i = 0; i < 2; ++i) {
;       int bo = tid * 16 + i * 4096, r = bo >> 6, c = (bo & 63) >> 1;
;       __builtin_amdgcn_global_load_lds((const unsigned*)(Bt + (size_t)r * ldb + kt * 32 + c), (__attribute__((address_space(3))) unsigned*)(SB + bo), 16, 0, 0);
;     }
;   };
;   asm volatile("s_waitcnt vmcnt(0)" ::: "memory");
;   __syncthreads();
;   stage(0, 0);
;   stage(1, 1);
;   const unsigned lbase = (unsigned)(size_t)(const __attribute__((address_space(3))) char*)smem;
;   const unsigned aoff = lbase + (wr * 128 + fr) * 64 + fq * 16, boff = lbase + 16384 + (wc * 64 + fr) * 64 + fq * 16;
.LBB0_1241:
	s_and_b32 s6, s3, 7
	s_lshl_b32 s6, s6, 19
	s_and_b32 s7, s24, 7
	s_add_i32 s25, s16, s6
	s_or_b32 s7, s7, s4
	v_mov_b32_e32 v144, v0
	s_lshr_b32 s28, s25, 5
	s_ashr_i32 s6, s24, 3
	s_lshl_b32 s7, s7, 14
	s_mov_b64 s[26:27], s[54:55]
	s_add_u32 s10, s26, s7
	v_ashrrev_i32_e32 v2, 2, v144
	v_lshlrev_b32_e32 v148, 4, v144
	v_ashrrev_i32_e32 v3, 31, v2
	s_addc_u32 s11, s27, 0
	s_ashr_i32 s7, s6, 31
	v_lshlrev_b64 v[2:3], 12, v[2:3]
	v_lshrrev_b64 v[246:247], 6, v[2:3]
	s_mov_b64 s[32:33], 0x100000
	s_mov_b64 s[34:35], 0x20000
	v_add_u32_e32 v10, 0x1000, v148
	s_lshl_b64 s[8:9], s[6:7], 13
	v_lshl_add_u64 v[4:5], s[10:11], 0, v[246:247]
	v_and_b32_e32 v134, 48, v148
	v_and_b32_e32 v253, 32, v144
	v_xor_b32_e32 v134, v134, v253
	v_readfirstlane_b32 s7, v148
	v_ashrrev_i32_e32 v6, 6, v10
	v_add_u32_e32 v14, 0x2000, v148
	v_lshl_add_u64 v[4:5], v[4:5], 0, v[134:135]
	s_mov_b32 m0, s7
	v_ashrrev_i32_e32 v7, 31, v6
	v_readfirstlane_b32 s7, v10
	v_ashrrev_i32_e32 v10, 6, v14
	v_add_u32_e32 v18, 0x3000, v148
	v_readlane_b32 s36, v254, 4
	s_waitcnt vmcnt(0)
	s_barrier
; template <class AF, class EPI>
; DEV void gemm_tile256(AF aptr, const u16* Bt, int ldb, int K, EPI epi, char* smem) {
;     ...
;   f32x4 acc[8][4];
; #pragma unroll
;   for (int m = 0; m < 8; ++m)
; #pragma unroll
;     for (int n = 0; n < 4; ++n) acc[m][n] = f32x4{0.f, 0.f, 0.f, 0.f};
;   const int nk = K / 32;
;   auto stage = [&](int kt, int buf) {
;     char* SA = smem + buf * 24576;
;     char* SB = SA + 16384;
; #pragma unroll
;     for (int i = 0; i < 4; ++i) {
;       int bo = tid * 16 + i * 4096, r = bo >> 6, c = (bo & 63) >> 1;
;       __builtin_amdgcn_global_load_lds((const unsigned*)aptr(r, kt * 32 + c), (__attribute__((address_space(3))) unsigned*)(SA + bo), 16, 0, 0);
;     }
; #pragma unroll
;     for (int i = 0; i < 2; ++i) {
;       int bo = tid * 16 + i * 4096, r = bo >> 6, c = (bo & 63) >> 1;
;       __builtin_amdgcn_global_load_lds((const unsigned*)(Bt + (size_t)r * ldb + kt * 32 + c), (__attribute__((address_space(3))) unsigned*)(SB + bo), 16, 0, 0);
;     }
;   };
;   asm volatile("s_waitcnt vmcnt(0)" ::: "memory");
;   __syncthreads();
;   stage(0, 0);
;   stage(1, 1);
;   const unsigned lbase = (unsigned)(size_t)(const __attribute__((address_space(3))) char*)smem;
;   const unsigned aoff = lbase + (wr * 128 + fr) * 64 + fq * 16, boff = lbase + 16384 + (wc * 64 + fr) * 64 + fq * 16;
	global_load_lds_dwordx4 v[4:5], off
	v_lshlrev_b64 v[6:7], 12, v[6:7]
	v_lshrrev_b64 v[248:249], 6, v[6:7]
	s_mov_b32 m0, s7
	v_ashrrev_i32_e32 v11, 31, v10
	v_readfirstlane_b32 s7, v14
	v_ashrrev_i32_e32 v14, 6, v18
	v_readlane_b32 s48, v254, 16
	v_lshl_add_u64 v[8:9], s[10:11], 0, v[248:249]
	v_lshlrev_b64 v[10:11], 6, v[10:11]
	v_ashrrev_i32_e32 v15, 31, v14
	v_readlane_b32 s49, v254, 17
	s_add_u32 s26, s48, s8
	v_lshl_add_u64 v[8:9], v[8:9], 0, v[134:135]
	v_lshl_add_u64 v[12:13], s[10:11], 0, v[10:11]
	v_lshlrev_b64 v[14:15], 6, v[14:15]
	s_addc_u32 s27, s49, s9
	global_load_lds_dwordx4 v[8:9], off
	v_lshl_add_u64 v[12:13], v[12:13], 0, v[134:135]
	s_mov_b32 m0, s7
	v_lshl_add_u64 v[16:17], s[10:11], 0, v[14:15]
	v_readfirstlane_b32 s7, v18
	v_add_u32_e32 v20, 0x4000, v148
	global_load_lds_dwordx4 v[12:13], off
	v_lshl_add_u64 v[16:17], v[16:17], 0, v[134:135]
	s_mov_b32 m0, s7
	v_lshl_add_u64 v[18:19], s[26:27], 0, v[246:247]
	v_readfirstlane_b32 s7, v20
	v_add_u32_e32 v22, 0x5000, v148
	global_load_lds_dwordx4 v[16:17], off
	v_lshl_add_u64 v[18:19], v[18:19], 0, v[134:135]
	s_mov_b32 m0, s7
	v_lshl_add_u64 v[20:21], s[26:27], 0, v[248:249]
	v_readfirstlane_b32 s7, v22
	v_add_u32_e32 v22, 0x6000, v148
	global_load_lds_dwordx4 v[18:19], off
	v_lshl_add_u64 v[20:21], v[20:21], 0, v[134:135]
	s_mov_b32 m0, s7
	v_readfirstlane_b32 s7, v22
	global_load_lds_dwordx4 v[20:21], off
	v_lshl_add_u64 v[4:5], v[4:5], 0, s[32:33]
	s_mov_b32 m0, s7
	s_add_u32 s10, s14, s28
	global_load_lds_dwordx4 v[4:5], off
	v_lshl_add_u64 v[4:5], v[8:9], 0, s[32:33]
	v_add_u32_e32 v8, 0x7000, v148
	v_bfe_u32 v147, v144, 4, 2
	v_readfirstlane_b32 s7, v8
	v_add_u32_e32 v8, 0x8000, v148
	s_mov_b32 m0, s7
	v_readfirstlane_b32 s7, v8
	v_add_u32_e32 v8, 0x9000, v148
	global_load_lds_dwordx4 v[4:5], off
	v_lshl_add_u64 v[4:5], v[12:13], 0, s[32:33]
	s_mov_b32 m0, s7
	v_readfirstlane_b32 s7, v8
	v_add_u32_e32 v8, 0xa000, v148
	global_load_lds_dwordx4 v[4:5], off
	v_lshl_add_u64 v[4:5], v[16:17], 0, s[32:33]
	s_mov_b32 m0, s7
	v_readfirstlane_b32 s7, v8
	v_add_u32_e32 v8, 0xb000, v148
	global_load_lds_dwordx4 v[4:5], off
	v_lshl_add_u64 v[4:5], v[18:19], 0, s[34:35]
	s_mov_b32 m0, s7
	v_readfirstlane_b32 s7, v8
	global_load_lds_dwordx4 v[4:5], off
	v_lshl_add_u64 v[4:5], v[20:21], 0, s[34:35]
	s_mov_b32 m0, s7
	s_addc_u32 s11, s15, 0
	global_load_lds_dwordx4 v[4:5], off
	v_bfe_u32 v145, v144, 6, 1
	v_ashrrev_i32_e32 v1, 7, v144
	v_and_b32_e32 v146, 15, v144
	v_lshlrev_b32_e32 v8, 4, v147
	v_lshlrev_b32_e32 v253, 2, v144
	v_and_b32_e32 v253, 32, v253
	v_xor_b32_e32 v8, v8, v253
	s_add_u32 s8, s17, s8
	v_lshlrev_b32_e32 v4, 13, v1
	v_lshlrev_b32_e32 v5, 6, v146
	v_lshl_or_b32 v9, v145, 12, v8
	v_or_b32_e32 v2, v2, v134
	v_or_b32_e32 v6, v6, v134
	v_or_b32_e32 v10, v10, v134
	v_or_b32_e32 v14, v14, v134
	s_addc_u32 s9, s18, s9
	v_or3_b32 v149, v4, v8, v5
	v_or3_b32 v150, v5, v9, s19
	v_or_b32_e32 v246, v246, v134
	v_or_b32_e32 v248, v248, v134
	v_lshl_add_u64 v[130:131], s[10:11], 0, v[246:247]
	v_lshl_add_u64 v[132:133], s[10:11], 0, v[248:249]
	v_lshl_add_u64 v[136:137], s[10:11], 0, v[10:11]
	v_lshl_add_u64 v[138:139], s[10:11], 0, v[14:15]
	v_lshl_add_u64 v[140:141], s[8:9], 0, v[248:249]
	v_lshl_add_u64 v[142:143], s[8:9], 0, v[246:247]
	s_mov_b64 s[8:9], 0
	s_mov_b32 s7, 0
	s_mov_b32 s26, 0
	v_mov_b32_e32 v2, 0
	v_mov_b32_e32 v3, v135
	v_mov_b32_e32 v4, v135
	v_mov_b32_e32 v5, v135
	v_mov_b32_e32 v6, 0
	v_mov_b32_e32 v7, v135
	v_mov_b32_e32 v8, v135
	v_mov_b32_e32 v9, v135
	v_mov_b32_e32 v10, 0
	v_mov_b32_e32 v11, v135
	v_mov_b32_e32 v12, v135
	v_mov_b32_e32 v13, v135
	v_mov_b32_e32 v14, 0
	v_mov_b32_e32 v15, v135
	v_mov_b32_e32 v16, v135
	v_mov_b32_e32 v17, v135
	v_mov_b32_e32 v18, 0
	v_mov_b32_e32 v19, v135
	v_mov_b32_e32 v20, v135
	v_mov_b32_e32 v21, v135
	v_mov_b32_e32 v22, 0
	v_mov_b32_e32 v23, v135
	v_mov_b32_e32 v24, v135
	v_mov_b32_e32 v25, v135
	v_mov_b32_e32 v26, 0
	v_mov_b32_e32 v27, v135
	v_mov_b32_e32 v28, v135
	v_mov_b32_e32 v29, v135
	v_mov_b32_e32 v30, 0
	v_mov_b32_e32 v31, v135
	v_mov_b32_e32 v32, v135
	v_mov_b32_e32 v33, v135
	v_mov_b32_e32 v34, 0
	v_mov_b32_e32 v35, v135
	v_mov_b32_e32 v36, v135
	v_mov_b32_e32 v37, v135
	v_mov_b32_e32 v38, 0
	v_mov_b32_e32 v39, v135
	v_mov_b32_e32 v40, v135
	v_mov_b32_e32 v41, v135
	v_mov_b32_e32 v42, 0
	v_mov_b32_e32 v43, v135
	v_mov_b32_e32 v44, v135
	v_mov_b32_e32 v45, v135
	v_mov_b32_e32 v94, 0
	v_mov_b32_e32 v95, v135
	v_mov_b32_e32 v96, v135
	v_mov_b32_e32 v97, v135
	v_mov_b32_e32 v98, 0
	v_mov_b32_e32 v99, v135
	v_mov_b32_e32 v100, v135
	v_mov_b32_e32 v101, v135
	v_mov_b32_e32 v102, 0
	v_mov_b32_e32 v103, v135
	v_mov_b32_e32 v104, v135
	v_mov_b32_e32 v105, v135
	v_mov_b32_e32 v106, 0
	v_mov_b32_e32 v107, v135
	v_mov_b32_e32 v108, v135
	v_mov_b32_e32 v109, v135
	v_mov_b32_e32 v110, 0
	v_mov_b32_e32 v111, v135
	v_mov_b32_e32 v112, v135
	v_mov_b32_e32 v113, v135
	v_mov_b32_e32 v114, 0
	v_mov_b32_e32 v115, v135
	v_mov_b32_e32 v116, v135
	v_mov_b32_e32 v117, v135
	v_mov_b32_e32 v118, 0
	v_mov_b32_e32 v119, v135
	v_mov_b32_e32 v120, v135
	v_mov_b32_e32 v121, v135
	v_mov_b32_e32 v122, 0
	v_mov_b32_e32 v123, v135
	v_mov_b32_e32 v124, v135
	v_mov_b32_e32 v125, v135
	v_mov_b32_e32 v126, 0
	v_mov_b32_e32 v127, v135
	v_mov_b32_e32 v128, v135
	v_mov_b32_e32 v129, v135
	v_mov_b32_e32 v46, 0
	v_mov_b32_e32 v47, v135
	v_mov_b32_e32 v48, v135
	v_mov_b32_e32 v49, v135
	v_mov_b32_e32 v50, 0
	v_mov_b32_e32 v51, v135
	v_mov_b32_e32 v52, v135
	v_mov_b32_e32 v53, v135
	v_mov_b32_e32 v54, 0
	v_mov_b32_e32 v55, v135
	v_mov_b32_e32 v56, v135
	v_mov_b32_e32 v57, v135
	v_mov_b32_e32 v58, 0
	v_mov_b32_e32 v59, v135
	v_mov_b32_e32 v60, v135
	v_mov_b32_e32 v61, v135
	v_mov_b32_e32 v62, 0
	v_mov_b32_e32 v63, v135
	v_mov_b32_e32 v64, v135
	v_mov_b32_e32 v65, v135
	v_mov_b32_e32 v66, 0
	v_mov_b32_e32 v67, v135
	v_mov_b32_e32 v68, v135
	v_mov_b32_e32 v69, v135
	v_mov_b32_e32 v70, 0
	v_mov_b32_e32 v71, v135
	v_mov_b32_e32 v72, v135
	v_mov_b32_e32 v73, v135
	v_mov_b32_e32 v74, 0
	v_mov_b32_e32 v75, v135
	v_mov_b32_e32 v76, v135
	v_mov_b32_e32 v77, v135
	v_mov_b32_e32 v78, 0
	v_mov_b32_e32 v79, v135
	v_mov_b32_e32 v80, v135
	v_mov_b32_e32 v81, v135
	v_mov_b32_e32 v82, 0
	v_mov_b32_e32 v83, v135
	v_mov_b32_e32 v84, v135
	v_mov_b32_e32 v85, v135
	v_mov_b32_e32 v86, 0
	v_mov_b32_e32 v87, v135
	v_mov_b32_e32 v88, v135
	v_mov_b32_e32 v89, v135
	v_mov_b32_e32 v90, 0
	v_mov_b32_e32 v91, v135
	v_mov_b32_e32 v92, v135
	v_mov_b32_e32 v93, v135
	v_readlane_b32 s37, v254, 5
	v_readlane_b32 s38, v254, 6
	v_readlane_b32 s39, v254, 7
	v_readlane_b32 s40, v254, 8
	v_readlane_b32 s41, v254, 9
	v_readlane_b32 s42, v254, 10
	v_readlane_b32 s43, v254, 11
	v_readlane_b32 s44, v254, 12
	v_readlane_b32 s45, v254, 13
	v_readlane_b32 s46, v254, 14
	v_readlane_b32 s47, v254, 15
	v_readlane_b32 s50, v254, 18
	v_readlane_b32 s51, v254, 19
	s_branch .LBB0_1243
	.p2align 6

; DEV int ltid() { int t = threadIdx.x; asm volatile("" : "+v"(t)); return t; }
; template <class AF, class EPI>
; DEV void gemm_tile256(AF aptr, const u16* Bt, int ldb, int K, EPI epi, char* smem) {
;   const int tid = ltid(), wid = tid >> 6, lane = tid & 63, wr = wid >> 1, wc = wid & 1, fr = lane & 15, fq = lane >> 4;
;   f32x4 acc[8][4];
; #pragma unroll
;   for (int m = 0; m < 8; ++m)
; #pragma unroll
;     for (int n = 0; n < 4; ++n) acc[m][n] = f32x4{0.f, 0.f, 0.f, 0.f};
;   const int nk = K / 32;
;   auto stage = [&](int kt, int buf) {
;     char* SA = smem + buf * 24576;
;     char* SB = SA + 16384;
; #pragma unroll
;     for (int i = 0; i < 4; ++i) {
;       int bo = tid * 16 + i * 4096, r = bo >> 6, c = (bo & 63) >> 1;
;       __builtin_amdgcn_global_load_lds((const unsigned*)aptr(r, kt * 32 + c), (__attribute__((address_space(3))) unsigned*)(SA + bo), 16, 0, 0);
;     }
; #pragma unroll
;     for (int i = 0; i < 2; ++i) {
;       int bo = tid * 16 + i * 4096, r = bo >> 6, c = (bo & 63) >> 1;
;       __builtin_amdgcn_global_load_lds((const unsigned*)(Bt + (size_t)r * ldb + kt * 32 + c), (__attribute__((address_space(3))) unsigned*)(SB + bo), 16, 0, 0);
;     }
;   };
;   asm volatile("s_waitcnt vmcnt(0)" ::: "memory");
;   __syncthreads();
;   stage(0, 0);
;   stage(1, 1);
;   const unsigned lbase = (unsigned)(size_t)(const __attribute__((address_space(3))) char*)smem;
;   const unsigned aoff = lbase + (wr * 128 + fr) * 64 + fq * 16, boff = lbase + 16384 + (wc * 64 + fr) * 64 + fq * 16;
.LBB0_1367:
	s_and_b32 s25, s2, 7
	s_lshl_b32 s0, s25, 19
	s_and_b32 s1, s58, 7
	s_add_i32 s0, s11, s0
	s_or_b32 s1, s1, s3
	v_mov_b32_e32 v144, v0
	s_lshr_b32 s28, s0, 5
	s_ashr_i32 s0, s58, 3
	s_lshl_b32 s1, s1, 14
	s_mov_b64 s[8:9], s[80:81]
	s_add_u32 s8, s8, s1
	v_ashrrev_i32_e32 v2, 2, v144
	v_lshlrev_b32_e32 v148, 4, v144
	v_ashrrev_i32_e32 v3, 31, v2
	s_addc_u32 s9, s9, 0
	s_ashr_i32 s1, s0, 31
	v_lshlrev_b64 v[2:3], 12, v[2:3]
	v_lshrrev_b64 v[246:247], 6, v[2:3]
	s_mov_b64 s[30:31], 0x100000
	s_mov_b64 s[32:33], 0x20000
	v_add_u32_e32 v10, 0x1000, v148
	s_lshl_b64 s[6:7], s[0:1], 13
	v_lshl_add_u64 v[4:5], s[8:9], 0, v[246:247]
	v_and_b32_e32 v130, 48, v148
	v_and_b32_e32 v253, 32, v144
	v_xor_b32_e32 v130, v130, v253
	v_readfirstlane_b32 s1, v148
	v_ashrrev_i32_e32 v6, 6, v10
	v_add_u32_e32 v14, 0x2000, v148
	v_lshl_add_u64 v[4:5], v[4:5], 0, v[130:131]
	s_mov_b32 m0, s1
	v_ashrrev_i32_e32 v7, 31, v6
	v_readfirstlane_b32 s1, v10
	v_ashrrev_i32_e32 v10, 6, v14
	v_add_u32_e32 v18, 0x3000, v148
	s_waitcnt vmcnt(0)
	s_barrier
; template <class AF, class EPI>
; DEV void gemm_tile256(AF aptr, const u16* Bt, int ldb, int K, EPI epi, char* smem) {
;     ...
;   f32x4 acc[8][4];
; #pragma unroll
;   for (int m = 0; m < 8; ++m)
; #pragma unroll
;     for (int n = 0; n < 4; ++n) acc[m][n] = f32x4{0.f, 0.f, 0.f, 0.f};
;   const int nk = K / 32;
;   auto stage = [&](int kt, int buf) {
;     char* SA = smem + buf * 24576;
;     char* SB = SA + 16384;
; #pragma unroll
;     for (int i = 0; i < 4; ++i) {
;       int bo = tid * 16 + i * 4096, r = bo >> 6, c = (bo & 63) >> 1;
;       __builtin_amdgcn_global_load_lds((const unsigned*)aptr(r, kt * 32 + c), (__attribute__((address_space(3))) unsigned*)(SA + bo), 16, 0, 0);
;     }
; #pragma unroll
;     for (int i = 0; i < 2; ++i) {
;       int bo = tid * 16 + i * 4096, r = bo >> 6, c = (bo & 63) >> 1;
;       __builtin_amdgcn_global_load_lds((const unsigned*)(Bt + (size_t)r * ldb + kt * 32 + c), (__attribute__((address_space(3))) unsigned*)(SB + bo), 16, 0, 0);
;     }
;   };
;   asm volatile("s_waitcnt vmcnt(0)" ::: "memory");
;   __syncthreads();
;   stage(0, 0);
;   stage(1, 1);
;   const unsigned lbase = (unsigned)(size_t)(const __attribute__((address_space(3))) char*)smem;
;   const unsigned aoff = lbase + (wr * 128 + fr) * 64 + fq * 16, boff = lbase + 16384 + (wc * 64 + fr) * 64 + fq * 16;
	global_load_lds_dwordx4 v[4:5], off
	v_lshlrev_b64 v[6:7], 12, v[6:7]
	v_lshrrev_b64 v[248:249], 6, v[6:7]
	s_mov_b32 m0, s1
	v_ashrrev_i32_e32 v11, 31, v10
	v_readfirstlane_b32 s1, v14
	v_ashrrev_i32_e32 v14, 6, v18
	v_lshl_add_u64 v[8:9], s[8:9], 0, v[248:249]
	v_lshlrev_b64 v[10:11], 6, v[10:11]
	v_ashrrev_i32_e32 v15, 31, v14
	s_add_u32 s26, s50, s6
	v_lshl_add_u64 v[8:9], v[8:9], 0, v[130:131]
	v_lshl_add_u64 v[12:13], s[8:9], 0, v[10:11]
	v_lshlrev_b64 v[14:15], 6, v[14:15]
	s_addc_u32 s27, s51, s7
	global_load_lds_dwordx4 v[8:9], off
	v_lshl_add_u64 v[12:13], v[12:13], 0, v[130:131]
	s_mov_b32 m0, s1
	v_lshl_add_u64 v[16:17], s[8:9], 0, v[14:15]
	v_readfirstlane_b32 s1, v18
	v_add_u32_e32 v20, 0x4000, v148
	global_load_lds_dwordx4 v[12:13], off
	v_lshl_add_u64 v[16:17], v[16:17], 0, v[130:131]
	s_mov_b32 m0, s1
	v_lshl_add_u64 v[18:19], s[26:27], 0, v[246:247]
	v_readfirstlane_b32 s1, v20
	v_add_u32_e32 v22, 0x5000, v148
	global_load_lds_dwordx4 v[16:17], off
	v_lshl_add_u64 v[18:19], v[18:19], 0, v[130:131]
	s_mov_b32 m0, s1
	v_lshl_add_u64 v[20:21], s[26:27], 0, v[248:249]
	v_readfirstlane_b32 s1, v22
	v_add_u32_e32 v22, 0x6000, v148
	global_load_lds_dwordx4 v[18:19], off
	v_lshl_add_u64 v[20:21], v[20:21], 0, v[130:131]
	s_mov_b32 m0, s1
	v_readfirstlane_b32 s1, v22
	global_load_lds_dwordx4 v[20:21], off
	v_lshl_add_u64 v[4:5], v[4:5], 0, s[30:31]
	s_mov_b32 m0, s1
	s_add_u32 s8, s5, s28
	global_load_lds_dwordx4 v[4:5], off
	v_lshl_add_u64 v[4:5], v[8:9], 0, s[30:31]
	v_add_u32_e32 v8, 0x7000, v148
	v_bfe_u32 v147, v144, 4, 2
	v_readfirstlane_b32 s1, v8
	v_add_u32_e32 v8, 0x8000, v148
	s_mov_b32 m0, s1
	v_readfirstlane_b32 s1, v8
	v_add_u32_e32 v8, 0x9000, v148
	global_load_lds_dwordx4 v[4:5], off
	v_lshl_add_u64 v[4:5], v[12:13], 0, s[30:31]
	s_mov_b32 m0, s1
	v_readfirstlane_b32 s1, v8
	v_add_u32_e32 v8, 0xa000, v148
	global_load_lds_dwordx4 v[4:5], off
	v_lshl_add_u64 v[4:5], v[16:17], 0, s[30:31]
	s_mov_b32 m0, s1
	v_readfirstlane_b32 s1, v8
	v_add_u32_e32 v8, 0xb000, v148
	global_load_lds_dwordx4 v[4:5], off
	v_lshl_add_u64 v[4:5], v[18:19], 0, s[32:33]
	s_mov_b32 m0, s1
	v_readfirstlane_b32 s1, v8
	global_load_lds_dwordx4 v[4:5], off
	v_lshl_add_u64 v[4:5], v[20:21], 0, s[32:33]
	s_mov_b32 m0, s1
	s_addc_u32 s9, s10, 0
	global_load_lds_dwordx4 v[4:5], off
	v_bfe_u32 v145, v144, 6, 1
	v_ashrrev_i32_e32 v1, 7, v144
	v_and_b32_e32 v146, 15, v144
	v_lshlrev_b32_e32 v8, 4, v147
	v_lshlrev_b32_e32 v253, 2, v144
	v_and_b32_e32 v253, 32, v253
	v_xor_b32_e32 v8, v8, v253
	s_add_u32 s6, s12, s6
	v_lshlrev_b32_e32 v4, 13, v1
	v_lshlrev_b32_e32 v5, 6, v146
	v_lshl_or_b32 v9, v145, 12, v8
	v_or_b32_e32 v2, v2, v130
	v_or_b32_e32 v6, v6, v130
	v_or_b32_e32 v10, v10, v130
	v_or_b32_e32 v14, v14, v130
	s_addc_u32 s7, s13, s7
	v_or3_b32 v149, v4, v8, v5
	v_or3_b32 v150, v5, v9, s15
	v_or_b32_e32 v246, v246, v130
	v_or_b32_e32 v248, v248, v130
	v_lshl_add_u64 v[132:133], s[8:9], 0, v[246:247]
	v_lshl_add_u64 v[134:135], s[8:9], 0, v[248:249]
	v_lshl_add_u64 v[136:137], s[8:9], 0, v[10:11]
	v_lshl_add_u64 v[138:139], s[8:9], 0, v[14:15]
	v_lshl_add_u64 v[140:141], s[6:7], 0, v[248:249]
	v_lshl_add_u64 v[142:143], s[6:7], 0, v[246:247]
	s_mov_b64 s[6:7], 0
	s_mov_b32 s1, 0
	s_mov_b32 s26, 0
	v_mov_b32_e32 v2, 0
	v_mov_b32_e32 v3, v131
	v_mov_b32_e32 v4, v131
	v_mov_b32_e32 v5, v131
	v_mov_b32_e32 v6, 0
	v_mov_b32_e32 v7, v131
	v_mov_b32_e32 v8, v131
	v_mov_b32_e32 v9, v131
	v_mov_b32_e32 v10, 0
	v_mov_b32_e32 v11, v131
	v_mov_b32_e32 v12, v131
	v_mov_b32_e32 v13, v131
	v_mov_b32_e32 v14, 0
	v_mov_b32_e32 v15, v131
	v_mov_b32_e32 v16, v131
	v_mov_b32_e32 v17, v131
	v_mov_b32_e32 v18, 0
	v_mov_b32_e32 v19, v131
	v_mov_b32_e32 v20, v131
	v_mov_b32_e32 v21, v131
	v_mov_b32_e32 v22, 0
	v_mov_b32_e32 v23, v131
	v_mov_b32_e32 v24, v131
	v_mov_b32_e32 v25, v131
	v_mov_b32_e32 v26, 0
	v_mov_b32_e32 v27, v131
	v_mov_b32_e32 v28, v131
	v_mov_b32_e32 v29, v131
	v_mov_b32_e32 v30, 0
	v_mov_b32_e32 v31, v131
	v_mov_b32_e32 v32, v131
	v_mov_b32_e32 v33, v131
	v_mov_b32_e32 v34, 0
	v_mov_b32_e32 v35, v131
	v_mov_b32_e32 v36, v131
	v_mov_b32_e32 v37, v131
	v_mov_b32_e32 v38, 0
	v_mov_b32_e32 v39, v131
	v_mov_b32_e32 v40, v131
	v_mov_b32_e32 v41, v131
	v_mov_b32_e32 v42, 0
	v_mov_b32_e32 v43, v131
	v_mov_b32_e32 v44, v131
	v_mov_b32_e32 v45, v131
	v_mov_b32_e32 v94, 0
	v_mov_b32_e32 v95, v131
	v_mov_b32_e32 v96, v131
	v_mov_b32_e32 v97, v131
	v_mov_b32_e32 v98, 0
	v_mov_b32_e32 v99, v131
	v_mov_b32_e32 v100, v131
	v_mov_b32_e32 v101, v131
	v_mov_b32_e32 v102, 0
	v_mov_b32_e32 v103, v131
	v_mov_b32_e32 v104, v131
	v_mov_b32_e32 v105, v131
	v_mov_b32_e32 v106, 0
	v_mov_b32_e32 v107, v131
	v_mov_b32_e32 v108, v131
	v_mov_b32_e32 v109, v131
	v_mov_b32_e32 v110, 0
	v_mov_b32_e32 v111, v131
	v_mov_b32_e32 v112, v131
	v_mov_b32_e32 v113, v131
	v_mov_b32_e32 v114, 0
	v_mov_b32_e32 v115, v131
	v_mov_b32_e32 v116, v131
	v_mov_b32_e32 v117, v131
	v_mov_b32_e32 v118, 0
	v_mov_b32_e32 v119, v131
	v_mov_b32_e32 v120, v131
	v_mov_b32_e32 v121, v131
	v_mov_b32_e32 v122, 0
	v_mov_b32_e32 v123, v131
	v_mov_b32_e32 v124, v131
	v_mov_b32_e32 v125, v131
	v_mov_b32_e32 v126, 0
	v_mov_b32_e32 v127, v131
	v_mov_b32_e32 v128, v131
	v_mov_b32_e32 v129, v131
	v_mov_b32_e32 v46, 0
	v_mov_b32_e32 v47, v131
	v_mov_b32_e32 v48, v131
	v_mov_b32_e32 v49, v131
	v_mov_b32_e32 v50, 0
	v_mov_b32_e32 v51, v131
	v_mov_b32_e32 v52, v131
	v_mov_b32_e32 v53, v131
	v_mov_b32_e32 v54, 0
	v_mov_b32_e32 v55, v131
	v_mov_b32_e32 v56, v131
	v_mov_b32_e32 v57, v131
	v_mov_b32_e32 v58, 0
	v_mov_b32_e32 v59, v131
	v_mov_b32_e32 v60, v131
	v_mov_b32_e32 v61, v131
	v_mov_b32_e32 v62, 0
	v_mov_b32_e32 v63, v131
	v_mov_b32_e32 v64, v131
	v_mov_b32_e32 v65, v131
	v_mov_b32_e32 v66, 0
	v_mov_b32_e32 v67, v131
	v_mov_b32_e32 v68, v131
	v_mov_b32_e32 v69, v131
	v_mov_b32_e32 v70, 0
	v_mov_b32_e32 v71, v131
	v_mov_b32_e32 v72, v131
	v_mov_b32_e32 v73, v131
	v_mov_b32_e32 v74, 0
	v_mov_b32_e32 v75, v131
	v_mov_b32_e32 v76, v131
	v_mov_b32_e32 v77, v131
	v_mov_b32_e32 v78, 0
	v_mov_b32_e32 v79, v131
	v_mov_b32_e32 v80, v131
	v_mov_b32_e32 v81, v131
	v_mov_b32_e32 v82, 0
	v_mov_b32_e32 v83, v131
	v_mov_b32_e32 v84, v131
	v_mov_b32_e32 v85, v131
	v_mov_b32_e32 v86, 0
	v_mov_b32_e32 v87, v131
	v_mov_b32_e32 v88, v131
	v_mov_b32_e32 v89, v131
	v_mov_b32_e32 v90, 0
	v_mov_b32_e32 v91, v131
	v_mov_b32_e32 v92, v131
	v_mov_b32_e32 v93, v131
	s_branch .LBB0_1369
	.p2align 6

; DEV int ltid() { int t = threadIdx.x; asm volatile("" : "+v"(t)); return t; }
; DEV float bflo(unsigned u) { return __uint_as_float(u << 16); }
; DEV float bfhi(unsigned u) { return __uint_as_float(u & 0xffff0000u); }
; DEV void peer_gather_token(const Params& p, int tok) {
;   const int lane = ltid() & 63, b = tok >> 11;
;   float hx[32], acc[32];
;   {
;     const u16* hr = p.h + (size_t)tok * 2048 + lane * 32;
; #pragma unroll
;     for (int q = 0; q < 4; ++q) {
;       u32x4 v = *(const u32x4*)(hr + q * 8);
; #pragma unroll
;       for (int e = 0; e < 4; ++e) { hx[q * 8 + 2 * e] = bflo(v[e]); hx[q * 8 + 2 * e + 1] = bfhi(v[e]); }
;     }
;   }
; #pragma unroll
;   for (int e = 0; e < 32; ++e) acc[e] = 0.f;
;   const int e0 = p.eidx[(size_t)tok * 128 + lane], e1 = p.eidx[(size_t)tok * 128 + 64 + lane];
;   const int g0 = __builtin_bit_cast(int, p.gw[(size_t)tok * 128 + lane]), g1 = __builtin_bit_cast(int, p.gw[(size_t)tok * 128 + 64 + lane]);
;   u32x2 dn[4][3], up[4][3];
;   auto issue = [&](int k, int slot) {
;     const int e = (k < 64) ? __builtin_amdgcn_readlane(e0, k) : __builtin_amdgcn_readlane(e1, k - 64);
;     const unsigned char* dr = p.down8 + (size_t)e * ROW6 + lane * 24;
;     const unsigned char* ur = p.up8 + (size_t)e * ROW6 + lane * 24;
; #pragma unroll
;     for (int i = 0; i < 3; ++i) { dn[slot][i] = *(const u32x2*)(dr + i * 8); up[slot][i] = *(const u32x2*)(ur + i * 8); }
;   };
;   issue(0, 0); issue(1, 1); issue(2, 2);
; #pragma unroll 1
;   for (int k4 = 0; k4 < 128; k4 += 4) {
.Lp12_token:
	.p2align 6
